# scan: mid-chunk workgroup barrier lets the consumer fetch and MFMA-expand the next chunk's first steps during steps 29-31 (no per-chunk prologue)
# baseline (speedup 1.0000x reference)
; #define YRED4(dst) { \
;           float a0 = b3 ? p2 : p0, a1 = b3 ? p3 : p1; const float s0 = b3 ? p0 : p2, s1 = b3 ? p1 : p3; \
;           a0 += dppf<0x128>(s0); a1 += dppf<0x128>(s1); \
;           float cc = b2 ? a1 : a0; const float dd = b2 ? a0 : a1; \
;           cc += dppf<0x141>(dd); cc += dppf<0xB1>(cc); cc += dppf<0x4E>(cc); dst = cc; }
; __device__ __forceinline__ void phase_scan(KP p) {
;     ...
;       } else if (c >= 0) {
;         const int buf = c & 1;
;         const float* fbase = feat + (buf * 32) * 320 + cs * 4;
;         const float* vb4 = vbuf + (buf * 16 + rowl) * 32;
;         const bool b3 = (cs & 8) != 0, b2 = (cs & 4) != 0;
;         float* yb = ybuf + (buf * 32 + (b3 ? 2 : 0) + (b2 ? 1 : 0)) * 16 + rowl;
;         float4 Ar, Aw, Ak, An, Ab, Br, Bw, Bk, Bn, Bb, Cr, Cw, Ck, Cn, Cb, Dr, Dw, Dk, Dn, Db;
;         float4 vcur = *(const float4*)vb4, vnext;
;         float q0 = 0.f, q1 = 0.f, q2 = 0.f, q3 = 0.f, p0 = 0.f, p1 = 0.f, p2 = 0.f, p3 = 0.f;
;     ...
;         SLD(A, 0); SLD(B, 1);
;         for (int g = 0; g < 8; ++g) {
;           const int st = g * 4;
;           SLD(C, st + 2); vnext = *(const float4*)(vb4 + st + 4);
;           __builtin_amdgcn_sched_barrier(0);
;           if (g > 0) { float yv; YRED4(yv); yb[(st - 4) * 16] = yv; }
;           SCOMP(A, vcur.x, q0);
;           SLD(D, st + 3);
;           __builtin_amdgcn_sched_barrier(0);
;           SCOMP(B, vcur.y, q1);
;           SLD(A, st + 4);
;           __builtin_amdgcn_sched_barrier(0);
;           SCOMP(C, vcur.z, q2);
;           SLD(B, st + 5);
;           __builtin_amdgcn_sched_barrier(0);
;           SCOMP(D, vcur.w, q3);
;           vcur = vnext; p0 = q0; p1 = q1; p2 = q2; p3 = q3;
;         }
;         { float yv; YRED4(yv); yb[28 * 16] = yv; }
.LBB0_769:
	s_or_b64 exec, exec, s[72:73]
	s_waitcnt lgkmcnt(0)
	s_barrier
.LBB0_770:
	s_or_saveexec_b64 s[50:51], s[70:71]
	s_movk_i32 s71, 0x600
	s_xor_b64 exec, exec, s[50:51]
	s_cbranch_execz .LBB0_755
	s_cmp_lt_i32 s18, 0
	s_cbranch_scc1 .Lscan_skipmid
	s_and_b32 s70, s18, 1
	s_cmp_lg_u32 s18, 0
	s_cbranch_scc1 .Lscan_hot
	v_and_b32_e32 v93, 63, v135
	v_bfe_u32 v94, v93, 3, 2
	v_and_b32_e32 v95, 3, v93
	v_lshl_add_u32 v94, v94, 2, v95
	v_lshrrev_b32_e32 v95, 5, v93
	v_lshl_add_u32 v94, v94, 1, v95
	s_mov_b32 s19, 0x16000
	v_lshl_add_u32 v129, v94, 4, s19
	v_and_b32_e32 v94, 15, v93
	v_lshlrev_b32_e32 v95, 3, v95
	v_sub_u32_e32 v94, v94, v95
	v_and_b32_e32 v95, 1, v94
	v_lshlrev_b32_e32 v95, 4, v95
	v_mov_b32_e32 v93, 0x3f80
	v_lshlrev_b32_e32 v93, v95, v93
	v_lshrrev_b32_e32 v94, 1, v94
	v_cmp_eq_u32_e64 s[74:75], 0, v94
	s_nop 1
	v_cndmask_b32_e64 v124, 0, v93, s[74:75]
	v_cmp_eq_u32_e64 s[74:75], 1, v94
	s_nop 1
	v_cndmask_b32_e64 v125, 0, v93, s[74:75]
	v_cmp_eq_u32_e64 s[74:75], 2, v94
	s_nop 1
	v_cndmask_b32_e64 v126, 0, v93, s[74:75]
	v_cmp_eq_u32_e64 s[74:75], 3, v94
	s_nop 1
	v_cndmask_b32_e64 v127, 0, v93, s[74:75]
	s_mul_i32 s19, s70, 0x4400
	v_add_u32_e32 v128, s19, v129
	s_mul_i32 s19, s70, 0xa000
	v_lshl_add_u32 v106, s70, 11, v121
	v_add_u32_e32 v105, s19, v120
	v_lshl_add_u32 v107, s70, 11, v146
	ds_read_b128 v[108:111], v128
	ds_read_b128 v[112:115], v128 offset:544
	ds_read_b128 v[80:83], v106
	ds_read_b128 v[16:19], v105 offset:256
	ds_read_b128 v[36:39], v105 offset:1536
	s_waitcnt lgkmcnt(4)
	v_mfma_f32_32x32x16_bf16 v[0:15], v[108:111], v[124:127], 0
	s_waitcnt lgkmcnt(3)
	v_mfma_f32_32x32x16_bf16 v[20:35], v[112:115], v[124:127], 0
	ds_read_b128 v[108:111], v128 offset:1088
	s_nop 7
	s_nop 3
	s_waitcnt lgkmcnt(0)
	s_branch .Lscan_go
.Lscan_hot:
	s_mul_i32 s19, s70, 0x4400
	v_add_u32_e32 v128, s19, v129
	s_mul_i32 s19, s70, 0xa000
	v_lshl_add_u32 v106, s70, 11, v121
	v_add_u32_e32 v105, s19, v120
	v_lshl_add_u32 v107, s70, 11, v146
.Lscan_go:
	v_pk_mul_f32 v[84:85], v[116:117], v[8:9]
	v_pk_mul_f32 v[86:87], v[80:81], v[4:5] op_sel_hi:[0,1]
	v_pk_fma_f32 v[84:85], v[118:119], v[10:11], v[84:85]
	v_pk_mul_f32 v[88:89], v[80:81], v[6:7] op_sel_hi:[0,1]
	v_add_f32_e32 v92, v84, v85
	v_pk_fma_f32 v[86:87], v[116:117], v[16:17], v[86:87]
	ds_read_b128 v[112:115], v128 offset:1632
	v_add_f32_dpp v92, v92, v92 quad_perm:[1,0,3,2] row_mask:0xf bank_mask:0xf bound_ctrl:1
	v_pk_fma_f32 v[88:89], v[118:119], v[18:19], v[88:89]
	v_mfma_f32_32x32x16_bf16 v[40:55], v[108:111], v[124:127], 0
	v_add_f32_dpp v92, v92, v92 quad_perm:[2,3,0,1] row_mask:0xf bank_mask:0xf bound_ctrl:1
	s_nop 1
	v_add_f32_dpp v92, v92, v92 row_half_mirror row_mask:0xf bank_mask:0xf bound_ctrl:1
	ds_read_b128 v[56:59], v105 offset:2816
	s_nop 0
	v_add_f32_dpp v92, v92, v92 row_mirror row_mask:0xf bank_mask:0xf bound_ctrl:1
	v_pk_fma_f32 v[116:117], v[12:13], v[92:93], v[86:87] op_sel_hi:[1,0,1]
	v_pk_fma_f32 v[118:119], v[14:15], v[92:93], v[88:89] op_sel_hi:[1,0,1]
	v_pk_mul_f32 v[84:85], v[116:117], v[28:29]
	v_pk_mul_f32 v[86:87], v[80:81], v[24:25] op_sel:[1,0]
	v_pk_fma_f32 v[84:85], v[118:119], v[30:31], v[84:85]
	v_pk_mul_f32 v[88:89], v[80:81], v[26:27] op_sel:[1,0]
	v_add_f32_e32 v92, v84, v85
	v_pk_fma_f32 v[86:87], v[116:117], v[36:37], v[86:87]
	v_pk_mul_f32 v[90:91], v[116:117], v[0:1]
	v_add_f32_dpp v92, v92, v92 quad_perm:[1,0,3,2] row_mask:0xf bank_mask:0xf bound_ctrl:1
	v_pk_fma_f32 v[88:89], v[118:119], v[38:39], v[88:89]
	v_pk_fma_f32 v[90:91], v[118:119], v[2:3], v[90:91]
	s_waitcnt lgkmcnt(1)
	v_mfma_f32_32x32x16_bf16 v[60:75], v[112:115], v[124:127], 0
	v_add_f32_dpp v92, v92, v92 quad_perm:[2,3,0,1] row_mask:0xf bank_mask:0xf bound_ctrl:1
	v_add_f32_e32 v96, v90, v91
	ds_read_b128 v[108:111], v128 offset:2176
	v_add_f32_dpp v92, v92, v92 row_half_mirror row_mask:0xf bank_mask:0xf bound_ctrl:1
	ds_read_b128 v[76:79], v105 offset:4096
	s_nop 0
	v_add_f32_dpp v92, v92, v92 row_mirror row_mask:0xf bank_mask:0xf bound_ctrl:1
	v_pk_fma_f32 v[116:117], v[32:33], v[92:93], v[86:87] op_sel_hi:[1,0,1]
	v_pk_fma_f32 v[118:119], v[34:35], v[92:93], v[88:89] op_sel_hi:[1,0,1]
	s_waitcnt lgkmcnt(2)
	v_pk_mul_f32 v[84:85], v[116:117], v[48:49]
	v_pk_mul_f32 v[86:87], v[82:83], v[44:45] op_sel_hi:[0,1]
	v_pk_fma_f32 v[84:85], v[118:119], v[50:51], v[84:85]
	v_pk_mul_f32 v[88:89], v[82:83], v[46:47] op_sel_hi:[0,1]
	v_add_f32_e32 v92, v84, v85
	v_pk_fma_f32 v[86:87], v[116:117], v[56:57], v[86:87]
	v_pk_mul_f32 v[90:91], v[116:117], v[20:21]
	v_add_f32_dpp v92, v92, v92 quad_perm:[1,0,3,2] row_mask:0xf bank_mask:0xf bound_ctrl:1
	v_pk_fma_f32 v[88:89], v[118:119], v[58:59], v[88:89]
	v_pk_fma_f32 v[90:91], v[118:119], v[22:23], v[90:91]
	s_waitcnt lgkmcnt(1)
	v_mfma_f32_32x32x16_bf16 v[0:15], v[108:111], v[124:127], 0
	v_add_f32_dpp v92, v92, v92 quad_perm:[2,3,0,1] row_mask:0xf bank_mask:0xf bound_ctrl:1
	v_add_f32_e32 v97, v90, v91
	ds_read_b128 v[112:115], v128 offset:2720
	v_add_f32_dpp v92, v92, v92 row_half_mirror row_mask:0xf bank_mask:0xf bound_ctrl:1
	ds_read_b128 v[16:19], v105 offset:5376
	s_nop 0
	v_add_f32_dpp v92, v92, v92 row_mirror row_mask:0xf bank_mask:0xf bound_ctrl:1
	v_pk_fma_f32 v[116:117], v[52:53], v[92:93], v[86:87] op_sel_hi:[1,0,1]
	v_pk_fma_f32 v[118:119], v[54:55], v[92:93], v[88:89] op_sel_hi:[1,0,1]
	s_waitcnt lgkmcnt(2)
; #define YRED4(dst) { \
;           float a0 = b3 ? p2 : p0, a1 = b3 ? p3 : p1; const float s0 = b3 ? p0 : p2, s1 = b3 ? p1 : p3; \
;           a0 += dppf<0x128>(s0); a1 += dppf<0x128>(s1); \
;           float cc = b2 ? a1 : a0; const float dd = b2 ? a0 : a1; \
;           cc += dppf<0x141>(dd); cc += dppf<0xB1>(cc); cc += dppf<0x4E>(cc); dst = cc; }
; __device__ __forceinline__ void phase_scan(KP p) {
;     ...
;         for (int g = 0; g < 8; ++g) {
;           const int st = g * 4;
;           SLD(C, st + 2); vnext = *(const float4*)(vb4 + st + 4);
;           __builtin_amdgcn_sched_barrier(0);
;           if (g > 0) { float yv; YRED4(yv); yb[(st - 4) * 16] = yv; }
;           SCOMP(A, vcur.x, q0);
;           SLD(D, st + 3);
;           __builtin_amdgcn_sched_barrier(0);
;           SCOMP(B, vcur.y, q1);
;           SLD(A, st + 4);
;           __builtin_amdgcn_sched_barrier(0);
;           SCOMP(C, vcur.z, q2);
;           SLD(B, st + 5);
;           __builtin_amdgcn_sched_barrier(0);
;           SCOMP(D, vcur.w, q3);
;           vcur = vnext; p0 = q0; p1 = q1; p2 = q2; p3 = q3;
;         }
	v_pk_mul_f32 v[84:85], v[116:117], v[68:69]
	v_pk_mul_f32 v[86:87], v[82:83], v[64:65] op_sel:[1,0]
	v_pk_fma_f32 v[84:85], v[118:119], v[70:71], v[84:85]
	v_pk_mul_f32 v[88:89], v[82:83], v[66:67] op_sel:[1,0]
	ds_read_b128 v[80:83], v106 offset:16
	v_add_f32_e32 v92, v84, v85
	v_pk_fma_f32 v[86:87], v[116:117], v[76:77], v[86:87]
	v_pk_mul_f32 v[90:91], v[116:117], v[40:41]
	v_add_f32_dpp v92, v92, v92 quad_perm:[1,0,3,2] row_mask:0xf bank_mask:0xf bound_ctrl:1
	v_pk_fma_f32 v[88:89], v[118:119], v[78:79], v[88:89]
	v_pk_fma_f32 v[90:91], v[118:119], v[42:43], v[90:91]
	s_waitcnt lgkmcnt(2)
	v_mfma_f32_32x32x16_bf16 v[20:35], v[112:115], v[124:127], 0
	v_add_f32_dpp v92, v92, v92 quad_perm:[2,3,0,1] row_mask:0xf bank_mask:0xf bound_ctrl:1
	v_add_f32_e32 v98, v90, v91
	ds_read_b128 v[108:111], v128 offset:3264
	v_add_f32_dpp v92, v92, v92 row_half_mirror row_mask:0xf bank_mask:0xf bound_ctrl:1
	ds_read_b128 v[36:39], v105 offset:6656
	s_nop 0
	v_add_f32_dpp v92, v92, v92 row_mirror row_mask:0xf bank_mask:0xf bound_ctrl:1
	v_pk_fma_f32 v[116:117], v[72:73], v[92:93], v[86:87] op_sel_hi:[1,0,1]
	v_pk_fma_f32 v[118:119], v[74:75], v[92:93], v[88:89] op_sel_hi:[1,0,1]
	s_waitcnt lgkmcnt(2)
	v_pk_mul_f32 v[84:85], v[116:117], v[8:9]
	v_pk_mul_f32 v[86:87], v[80:81], v[4:5] op_sel_hi:[0,1]
	v_pk_fma_f32 v[84:85], v[118:119], v[10:11], v[84:85]
	v_pk_mul_f32 v[88:89], v[80:81], v[6:7] op_sel_hi:[0,1]
	v_add_f32_e32 v92, v84, v85
	v_pk_fma_f32 v[86:87], v[116:117], v[16:17], v[86:87]
	v_pk_mul_f32 v[90:91], v[116:117], v[60:61]
	v_add_f32_dpp v92, v92, v92 quad_perm:[1,0,3,2] row_mask:0xf bank_mask:0xf bound_ctrl:1
	v_pk_fma_f32 v[88:89], v[118:119], v[18:19], v[88:89]
	v_pk_fma_f32 v[90:91], v[118:119], v[62:63], v[90:91]
	s_waitcnt lgkmcnt(1)
	v_mfma_f32_32x32x16_bf16 v[40:55], v[108:111], v[124:127], 0
	v_add_f32_dpp v92, v92, v92 quad_perm:[2,3,0,1] row_mask:0xf bank_mask:0xf bound_ctrl:1
	v_add_f32_e32 v99, v90, v91
	ds_read_b128 v[112:115], v128 offset:3808
	v_cndmask_b32_e64 v100, v98, v96, s[38:39]
	v_cndmask_b32_e64 v102, v96, v98, s[38:39]
	v_add_f32_dpp v92, v92, v92 row_half_mirror row_mask:0xf bank_mask:0xf bound_ctrl:1
	ds_read_b128 v[56:59], v105 offset:7936
	v_cndmask_b32_e64 v101, v99, v97, s[38:39]
	v_cndmask_b32_e64 v103, v97, v99, s[38:39]
	v_add_f32_dpp v92, v92, v92 row_mirror row_mask:0xf bank_mask:0xf bound_ctrl:1
	v_pk_fma_f32 v[116:117], v[12:13], v[92:93], v[86:87] op_sel_hi:[1,0,1]
	v_pk_fma_f32 v[118:119], v[14:15], v[92:93], v[88:89] op_sel_hi:[1,0,1]
	s_waitcnt lgkmcnt(2)
	v_pk_mul_f32 v[84:85], v[116:117], v[28:29]
	v_pk_mul_f32 v[86:87], v[80:81], v[24:25] op_sel:[1,0]
	v_pk_fma_f32 v[84:85], v[118:119], v[30:31], v[84:85]
	v_pk_mul_f32 v[88:89], v[80:81], v[26:27] op_sel:[1,0]
	v_add_f32_e32 v92, v84, v85
	v_pk_fma_f32 v[86:87], v[116:117], v[36:37], v[86:87]
	v_pk_mul_f32 v[90:91], v[116:117], v[0:1]
	v_add_f32_dpp v92, v92, v92 quad_perm:[1,0,3,2] row_mask:0xf bank_mask:0xf bound_ctrl:1
	v_pk_fma_f32 v[88:89], v[118:119], v[38:39], v[88:89]
	v_pk_fma_f32 v[90:91], v[118:119], v[2:3], v[90:91]
	s_waitcnt lgkmcnt(1)
	v_mfma_f32_32x32x16_bf16 v[60:75], v[112:115], v[124:127], 0
	v_add_f32_dpp v92, v92, v92 quad_perm:[2,3,0,1] row_mask:0xf bank_mask:0xf bound_ctrl:1
	v_add_f32_e32 v96, v90, v91
	ds_read_b128 v[108:111], v128 offset:4352
	v_add_f32_dpp v102, v102, v100 row_ror:8 row_mask:0xf bank_mask:0xf bound_ctrl:1
	v_add_f32_dpp v92, v92, v92 row_half_mirror row_mask:0xf bank_mask:0xf bound_ctrl:1
	ds_read_b128 v[76:79], v105 offset:9216
	v_add_f32_dpp v103, v103, v101 row_ror:8 row_mask:0xf bank_mask:0xf bound_ctrl:1
	v_add_f32_dpp v92, v92, v92 row_mirror row_mask:0xf bank_mask:0xf bound_ctrl:1
	v_cndmask_b32_e64 v104, v103, v102, s[40:41]
	v_cndmask_b32_e64 v102, v102, v103, s[40:41]
	v_pk_fma_f32 v[116:117], v[32:33], v[92:93], v[86:87] op_sel_hi:[1,0,1]
	v_pk_fma_f32 v[118:119], v[34:35], v[92:93], v[88:89] op_sel_hi:[1,0,1]
	s_waitcnt lgkmcnt(2)
	v_pk_mul_f32 v[84:85], v[116:117], v[48:49]
	v_pk_mul_f32 v[86:87], v[82:83], v[44:45] op_sel_hi:[0,1]
	v_pk_fma_f32 v[84:85], v[118:119], v[50:51], v[84:85]
	v_pk_mul_f32 v[88:89], v[82:83], v[46:47] op_sel_hi:[0,1]
	v_add_f32_e32 v92, v84, v85
	v_pk_fma_f32 v[86:87], v[116:117], v[56:57], v[86:87]
	v_pk_mul_f32 v[90:91], v[116:117], v[20:21]
	v_add_f32_dpp v92, v92, v92 quad_perm:[1,0,3,2] row_mask:0xf bank_mask:0xf bound_ctrl:1
	v_pk_fma_f32 v[88:89], v[118:119], v[58:59], v[88:89]
	v_pk_fma_f32 v[90:91], v[118:119], v[22:23], v[90:91]
	s_waitcnt lgkmcnt(1)
	v_mfma_f32_32x32x16_bf16 v[0:15], v[108:111], v[124:127], 0
	v_add_f32_dpp v92, v92, v92 quad_perm:[2,3,0,1] row_mask:0xf bank_mask:0xf bound_ctrl:1
	v_add_f32_e32 v97, v90, v91
	ds_read_b128 v[112:115], v128 offset:4896
	v_add_f32_dpp v92, v92, v92 row_half_mirror row_mask:0xf bank_mask:0xf bound_ctrl:1
	ds_read_b128 v[16:19], v105 offset:10496
	v_add_f32_dpp v102, v102, v104 row_half_mirror row_mask:0xf bank_mask:0xf bound_ctrl:1
	v_add_f32_dpp v92, v92, v92 row_mirror row_mask:0xf bank_mask:0xf bound_ctrl:1
	v_pk_fma_f32 v[116:117], v[52:53], v[92:93], v[86:87] op_sel_hi:[1,0,1]
	v_pk_fma_f32 v[118:119], v[54:55], v[92:93], v[88:89] op_sel_hi:[1,0,1]
	v_add_f32_dpp v102, v102, v102 quad_perm:[1,0,3,2] row_mask:0xf bank_mask:0xf bound_ctrl:1
	s_waitcnt lgkmcnt(2)
	v_pk_mul_f32 v[84:85], v[116:117], v[68:69]
	v_pk_mul_f32 v[86:87], v[82:83], v[64:65] op_sel:[1,0]
	v_pk_fma_f32 v[84:85], v[118:119], v[70:71], v[84:85]
	v_pk_mul_f32 v[88:89], v[82:83], v[66:67] op_sel:[1,0]
	ds_read_b128 v[80:83], v106 offset:32
	v_add_f32_e32 v92, v84, v85
	v_pk_fma_f32 v[86:87], v[116:117], v[76:77], v[86:87]
	v_pk_mul_f32 v[90:91], v[116:117], v[40:41]
	v_add_f32_dpp v92, v92, v92 quad_perm:[1,0,3,2] row_mask:0xf bank_mask:0xf bound_ctrl:1
	v_pk_fma_f32 v[88:89], v[118:119], v[78:79], v[88:89]
	v_pk_fma_f32 v[90:91], v[118:119], v[42:43], v[90:91]
	s_waitcnt lgkmcnt(2)
; #define YRED4(dst) { \
;           float a0 = b3 ? p2 : p0, a1 = b3 ? p3 : p1; const float s0 = b3 ? p0 : p2, s1 = b3 ? p1 : p3; \
;           a0 += dppf<0x128>(s0); a1 += dppf<0x128>(s1); \
;           float cc = b2 ? a1 : a0; const float dd = b2 ? a0 : a1; \
;           cc += dppf<0x141>(dd); cc += dppf<0xB1>(cc); cc += dppf<0x4E>(cc); dst = cc; }
; __device__ __forceinline__ void phase_scan(KP p) {
;     ...
;         for (int g = 0; g < 8; ++g) {
;           const int st = g * 4;
;           SLD(C, st + 2); vnext = *(const float4*)(vb4 + st + 4);
;           __builtin_amdgcn_sched_barrier(0);
;           if (g > 0) { float yv; YRED4(yv); yb[(st - 4) * 16] = yv; }
;           SCOMP(A, vcur.x, q0);
;           SLD(D, st + 3);
;           __builtin_amdgcn_sched_barrier(0);
;           SCOMP(B, vcur.y, q1);
;           SLD(A, st + 4);
;           __builtin_amdgcn_sched_barrier(0);
;           SCOMP(C, vcur.z, q2);
;           SLD(B, st + 5);
;           __builtin_amdgcn_sched_barrier(0);
;           SCOMP(D, vcur.w, q3);
;           vcur = vnext; p0 = q0; p1 = q1; p2 = q2; p3 = q3;
;         }
	v_mfma_f32_32x32x16_bf16 v[20:35], v[112:115], v[124:127], 0
	v_add_f32_dpp v92, v92, v92 quad_perm:[2,3,0,1] row_mask:0xf bank_mask:0xf bound_ctrl:1
	v_add_f32_e32 v98, v90, v91
	ds_read_b128 v[108:111], v128 offset:5440
	v_add_f32_dpp v92, v92, v92 row_half_mirror row_mask:0xf bank_mask:0xf bound_ctrl:1
	ds_read_b128 v[36:39], v105 offset:11776
	v_add_f32_dpp v102, v102, v102 quad_perm:[2,3,0,1] row_mask:0xf bank_mask:0xf bound_ctrl:1
	v_add_f32_dpp v92, v92, v92 row_mirror row_mask:0xf bank_mask:0xf bound_ctrl:1
	v_pk_fma_f32 v[116:117], v[72:73], v[92:93], v[86:87] op_sel_hi:[1,0,1]
	v_pk_fma_f32 v[118:119], v[74:75], v[92:93], v[88:89] op_sel_hi:[1,0,1]
	ds_write_b32 v107, v102
	s_waitcnt lgkmcnt(3)
	v_pk_mul_f32 v[84:85], v[116:117], v[8:9]
	v_pk_mul_f32 v[86:87], v[80:81], v[4:5] op_sel_hi:[0,1]
	v_pk_fma_f32 v[84:85], v[118:119], v[10:11], v[84:85]
	v_pk_mul_f32 v[88:89], v[80:81], v[6:7] op_sel_hi:[0,1]
	v_add_f32_e32 v92, v84, v85
	v_pk_fma_f32 v[86:87], v[116:117], v[16:17], v[86:87]
	v_pk_mul_f32 v[90:91], v[116:117], v[60:61]
	v_add_f32_dpp v92, v92, v92 quad_perm:[1,0,3,2] row_mask:0xf bank_mask:0xf bound_ctrl:1
	v_pk_fma_f32 v[88:89], v[118:119], v[18:19], v[88:89]
	v_pk_fma_f32 v[90:91], v[118:119], v[62:63], v[90:91]
	s_waitcnt lgkmcnt(2)
	v_mfma_f32_32x32x16_bf16 v[40:55], v[108:111], v[124:127], 0
	v_add_f32_dpp v92, v92, v92 quad_perm:[2,3,0,1] row_mask:0xf bank_mask:0xf bound_ctrl:1
	v_add_f32_e32 v99, v90, v91
	ds_read_b128 v[112:115], v128 offset:5984
	v_cndmask_b32_e64 v100, v98, v96, s[38:39]
	v_cndmask_b32_e64 v102, v96, v98, s[38:39]
	v_add_f32_dpp v92, v92, v92 row_half_mirror row_mask:0xf bank_mask:0xf bound_ctrl:1
	ds_read_b128 v[56:59], v105 offset:13056
	v_cndmask_b32_e64 v101, v99, v97, s[38:39]
	v_cndmask_b32_e64 v103, v97, v99, s[38:39]
	v_add_f32_dpp v92, v92, v92 row_mirror row_mask:0xf bank_mask:0xf bound_ctrl:1
	v_pk_fma_f32 v[116:117], v[12:13], v[92:93], v[86:87] op_sel_hi:[1,0,1]
	v_pk_fma_f32 v[118:119], v[14:15], v[92:93], v[88:89] op_sel_hi:[1,0,1]
	s_waitcnt lgkmcnt(3)
	v_pk_mul_f32 v[84:85], v[116:117], v[28:29]
	v_pk_mul_f32 v[86:87], v[80:81], v[24:25] op_sel:[1,0]
	v_pk_fma_f32 v[84:85], v[118:119], v[30:31], v[84:85]
	v_pk_mul_f32 v[88:89], v[80:81], v[26:27] op_sel:[1,0]
	v_add_f32_e32 v92, v84, v85
	v_pk_fma_f32 v[86:87], v[116:117], v[36:37], v[86:87]
	v_pk_mul_f32 v[90:91], v[116:117], v[0:1]
	v_add_f32_dpp v92, v92, v92 quad_perm:[1,0,3,2] row_mask:0xf bank_mask:0xf bound_ctrl:1
	v_pk_fma_f32 v[88:89], v[118:119], v[38:39], v[88:89]
	v_pk_fma_f32 v[90:91], v[118:119], v[2:3], v[90:91]
	s_waitcnt lgkmcnt(1)
	v_mfma_f32_32x32x16_bf16 v[60:75], v[112:115], v[124:127], 0
	v_add_f32_dpp v92, v92, v92 quad_perm:[2,3,0,1] row_mask:0xf bank_mask:0xf bound_ctrl:1
	v_add_f32_e32 v96, v90, v91
	ds_read_b128 v[108:111], v128 offset:6528
	v_add_f32_dpp v102, v102, v100 row_ror:8 row_mask:0xf bank_mask:0xf bound_ctrl:1
	v_add_f32_dpp v92, v92, v92 row_half_mirror row_mask:0xf bank_mask:0xf bound_ctrl:1
	ds_read_b128 v[76:79], v105 offset:14336
	v_add_f32_dpp v103, v103, v101 row_ror:8 row_mask:0xf bank_mask:0xf bound_ctrl:1
	v_add_f32_dpp v92, v92, v92 row_mirror row_mask:0xf bank_mask:0xf bound_ctrl:1
	v_cndmask_b32_e64 v104, v103, v102, s[40:41]
	v_cndmask_b32_e64 v102, v102, v103, s[40:41]
	v_pk_fma_f32 v[116:117], v[32:33], v[92:93], v[86:87] op_sel_hi:[1,0,1]
	v_pk_fma_f32 v[118:119], v[34:35], v[92:93], v[88:89] op_sel_hi:[1,0,1]
	s_waitcnt lgkmcnt(2)
	v_pk_mul_f32 v[84:85], v[116:117], v[48:49]
	v_pk_mul_f32 v[86:87], v[82:83], v[44:45] op_sel_hi:[0,1]
	v_pk_fma_f32 v[84:85], v[118:119], v[50:51], v[84:85]
	v_pk_mul_f32 v[88:89], v[82:83], v[46:47] op_sel_hi:[0,1]
	v_add_f32_e32 v92, v84, v85
	v_pk_fma_f32 v[86:87], v[116:117], v[56:57], v[86:87]
	v_pk_mul_f32 v[90:91], v[116:117], v[20:21]
	v_add_f32_dpp v92, v92, v92 quad_perm:[1,0,3,2] row_mask:0xf bank_mask:0xf bound_ctrl:1
	v_pk_fma_f32 v[88:89], v[118:119], v[58:59], v[88:89]
	v_pk_fma_f32 v[90:91], v[118:119], v[22:23], v[90:91]
	s_waitcnt lgkmcnt(1)
	v_mfma_f32_32x32x16_bf16 v[0:15], v[108:111], v[124:127], 0
	v_add_f32_dpp v92, v92, v92 quad_perm:[2,3,0,1] row_mask:0xf bank_mask:0xf bound_ctrl:1
	v_add_f32_e32 v97, v90, v91
	ds_read_b128 v[112:115], v128 offset:7072
	v_add_f32_dpp v92, v92, v92 row_half_mirror row_mask:0xf bank_mask:0xf bound_ctrl:1
	ds_read_b128 v[16:19], v105 offset:15616
	v_add_f32_dpp v102, v102, v104 row_half_mirror row_mask:0xf bank_mask:0xf bound_ctrl:1
	v_add_f32_dpp v92, v92, v92 row_mirror row_mask:0xf bank_mask:0xf bound_ctrl:1
	v_pk_fma_f32 v[116:117], v[52:53], v[92:93], v[86:87] op_sel_hi:[1,0,1]
	v_pk_fma_f32 v[118:119], v[54:55], v[92:93], v[88:89] op_sel_hi:[1,0,1]
	v_add_f32_dpp v102, v102, v102 quad_perm:[1,0,3,2] row_mask:0xf bank_mask:0xf bound_ctrl:1
	s_waitcnt lgkmcnt(2)
	v_pk_mul_f32 v[84:85], v[116:117], v[68:69]
	v_pk_mul_f32 v[86:87], v[82:83], v[64:65] op_sel:[1,0]
	v_pk_fma_f32 v[84:85], v[118:119], v[70:71], v[84:85]
	v_pk_mul_f32 v[88:89], v[82:83], v[66:67] op_sel:[1,0]
	ds_read_b128 v[80:83], v106 offset:48
	v_add_f32_e32 v92, v84, v85
	v_pk_fma_f32 v[86:87], v[116:117], v[76:77], v[86:87]
	v_pk_mul_f32 v[90:91], v[116:117], v[40:41]
	v_add_f32_dpp v92, v92, v92 quad_perm:[1,0,3,2] row_mask:0xf bank_mask:0xf bound_ctrl:1
	v_pk_fma_f32 v[88:89], v[118:119], v[78:79], v[88:89]
	v_pk_fma_f32 v[90:91], v[118:119], v[42:43], v[90:91]
	s_waitcnt lgkmcnt(2)
; #define YRED4(dst) { \
;           float a0 = b3 ? p2 : p0, a1 = b3 ? p3 : p1; const float s0 = b3 ? p0 : p2, s1 = b3 ? p1 : p3; \
;           a0 += dppf<0x128>(s0); a1 += dppf<0x128>(s1); \
;           float cc = b2 ? a1 : a0; const float dd = b2 ? a0 : a1; \
;           cc += dppf<0x141>(dd); cc += dppf<0xB1>(cc); cc += dppf<0x4E>(cc); dst = cc; }
; __device__ __forceinline__ void phase_scan(KP p) {
;     ...
;         for (int g = 0; g < 8; ++g) {
;           const int st = g * 4;
;           SLD(C, st + 2); vnext = *(const float4*)(vb4 + st + 4);
;           __builtin_amdgcn_sched_barrier(0);
;           if (g > 0) { float yv; YRED4(yv); yb[(st - 4) * 16] = yv; }
;           SCOMP(A, vcur.x, q0);
;           SLD(D, st + 3);
;           __builtin_amdgcn_sched_barrier(0);
;           SCOMP(B, vcur.y, q1);
;           SLD(A, st + 4);
;           __builtin_amdgcn_sched_barrier(0);
;           SCOMP(C, vcur.z, q2);
;           SLD(B, st + 5);
;           __builtin_amdgcn_sched_barrier(0);
;           SCOMP(D, vcur.w, q3);
;           vcur = vnext; p0 = q0; p1 = q1; p2 = q2; p3 = q3;
;         }
	v_mfma_f32_32x32x16_bf16 v[20:35], v[112:115], v[124:127], 0
	v_add_f32_dpp v92, v92, v92 quad_perm:[2,3,0,1] row_mask:0xf bank_mask:0xf bound_ctrl:1
	v_add_f32_e32 v98, v90, v91
	ds_read_b128 v[108:111], v128 offset:7616
	v_add_f32_dpp v92, v92, v92 row_half_mirror row_mask:0xf bank_mask:0xf bound_ctrl:1
	ds_read_b128 v[36:39], v105 offset:16896
	v_add_f32_dpp v102, v102, v102 quad_perm:[2,3,0,1] row_mask:0xf bank_mask:0xf bound_ctrl:1
	v_add_f32_dpp v92, v92, v92 row_mirror row_mask:0xf bank_mask:0xf bound_ctrl:1
	v_pk_fma_f32 v[116:117], v[72:73], v[92:93], v[86:87] op_sel_hi:[1,0,1]
	v_pk_fma_f32 v[118:119], v[74:75], v[92:93], v[88:89] op_sel_hi:[1,0,1]
	ds_write_b32 v107, v102 offset:256
	s_waitcnt lgkmcnt(3)
	v_pk_mul_f32 v[84:85], v[116:117], v[8:9]
	v_pk_mul_f32 v[86:87], v[80:81], v[4:5] op_sel_hi:[0,1]
	v_pk_fma_f32 v[84:85], v[118:119], v[10:11], v[84:85]
	v_pk_mul_f32 v[88:89], v[80:81], v[6:7] op_sel_hi:[0,1]
	v_add_f32_e32 v92, v84, v85
	v_pk_fma_f32 v[86:87], v[116:117], v[16:17], v[86:87]
	v_pk_mul_f32 v[90:91], v[116:117], v[60:61]
	v_add_f32_dpp v92, v92, v92 quad_perm:[1,0,3,2] row_mask:0xf bank_mask:0xf bound_ctrl:1
	v_pk_fma_f32 v[88:89], v[118:119], v[18:19], v[88:89]
	v_pk_fma_f32 v[90:91], v[118:119], v[62:63], v[90:91]
	s_waitcnt lgkmcnt(2)
	v_mfma_f32_32x32x16_bf16 v[40:55], v[108:111], v[124:127], 0
	v_add_f32_dpp v92, v92, v92 quad_perm:[2,3,0,1] row_mask:0xf bank_mask:0xf bound_ctrl:1
	v_add_f32_e32 v99, v90, v91
	ds_read_b128 v[112:115], v128 offset:8160
	v_cndmask_b32_e64 v100, v98, v96, s[38:39]
	v_cndmask_b32_e64 v102, v96, v98, s[38:39]
	v_add_f32_dpp v92, v92, v92 row_half_mirror row_mask:0xf bank_mask:0xf bound_ctrl:1
	ds_read_b128 v[56:59], v105 offset:18176
	v_cndmask_b32_e64 v101, v99, v97, s[38:39]
	v_cndmask_b32_e64 v103, v97, v99, s[38:39]
	v_add_f32_dpp v92, v92, v92 row_mirror row_mask:0xf bank_mask:0xf bound_ctrl:1
	v_pk_fma_f32 v[116:117], v[12:13], v[92:93], v[86:87] op_sel_hi:[1,0,1]
	v_pk_fma_f32 v[118:119], v[14:15], v[92:93], v[88:89] op_sel_hi:[1,0,1]
	s_waitcnt lgkmcnt(3)
	v_pk_mul_f32 v[84:85], v[116:117], v[28:29]
	v_pk_mul_f32 v[86:87], v[80:81], v[24:25] op_sel:[1,0]
	v_pk_fma_f32 v[84:85], v[118:119], v[30:31], v[84:85]
	v_pk_mul_f32 v[88:89], v[80:81], v[26:27] op_sel:[1,0]
	v_add_f32_e32 v92, v84, v85
	v_pk_fma_f32 v[86:87], v[116:117], v[36:37], v[86:87]
	v_pk_mul_f32 v[90:91], v[116:117], v[0:1]
	v_add_f32_dpp v92, v92, v92 quad_perm:[1,0,3,2] row_mask:0xf bank_mask:0xf bound_ctrl:1
	v_pk_fma_f32 v[88:89], v[118:119], v[38:39], v[88:89]
	v_pk_fma_f32 v[90:91], v[118:119], v[2:3], v[90:91]
	s_waitcnt lgkmcnt(1)
	v_mfma_f32_32x32x16_bf16 v[60:75], v[112:115], v[124:127], 0
	v_add_f32_dpp v92, v92, v92 quad_perm:[2,3,0,1] row_mask:0xf bank_mask:0xf bound_ctrl:1
	v_add_f32_e32 v96, v90, v91
	ds_read_b128 v[108:111], v128 offset:8704
	v_add_f32_dpp v102, v102, v100 row_ror:8 row_mask:0xf bank_mask:0xf bound_ctrl:1
	v_add_f32_dpp v92, v92, v92 row_half_mirror row_mask:0xf bank_mask:0xf bound_ctrl:1
	ds_read_b128 v[76:79], v105 offset:19456
	v_add_f32_dpp v103, v103, v101 row_ror:8 row_mask:0xf bank_mask:0xf bound_ctrl:1
	v_add_f32_dpp v92, v92, v92 row_mirror row_mask:0xf bank_mask:0xf bound_ctrl:1
	v_cndmask_b32_e64 v104, v103, v102, s[40:41]
	v_cndmask_b32_e64 v102, v102, v103, s[40:41]
	v_pk_fma_f32 v[116:117], v[32:33], v[92:93], v[86:87] op_sel_hi:[1,0,1]
	v_pk_fma_f32 v[118:119], v[34:35], v[92:93], v[88:89] op_sel_hi:[1,0,1]
	s_waitcnt lgkmcnt(2)
	v_pk_mul_f32 v[84:85], v[116:117], v[48:49]
	v_pk_mul_f32 v[86:87], v[82:83], v[44:45] op_sel_hi:[0,1]
	v_pk_fma_f32 v[84:85], v[118:119], v[50:51], v[84:85]
	v_pk_mul_f32 v[88:89], v[82:83], v[46:47] op_sel_hi:[0,1]
	v_add_f32_e32 v92, v84, v85
	v_pk_fma_f32 v[86:87], v[116:117], v[56:57], v[86:87]
	v_pk_mul_f32 v[90:91], v[116:117], v[20:21]
	v_add_f32_dpp v92, v92, v92 quad_perm:[1,0,3,2] row_mask:0xf bank_mask:0xf bound_ctrl:1
	v_pk_fma_f32 v[88:89], v[118:119], v[58:59], v[88:89]
	v_pk_fma_f32 v[90:91], v[118:119], v[22:23], v[90:91]
	s_waitcnt lgkmcnt(1)
	v_mfma_f32_32x32x16_bf16 v[0:15], v[108:111], v[124:127], 0
	v_add_f32_dpp v92, v92, v92 quad_perm:[2,3,0,1] row_mask:0xf bank_mask:0xf bound_ctrl:1
	v_add_f32_e32 v97, v90, v91
	ds_read_b128 v[112:115], v128 offset:9248
	v_add_f32_dpp v92, v92, v92 row_half_mirror row_mask:0xf bank_mask:0xf bound_ctrl:1
	ds_read_b128 v[16:19], v105 offset:20736
	v_add_f32_dpp v102, v102, v104 row_half_mirror row_mask:0xf bank_mask:0xf bound_ctrl:1
	v_add_f32_dpp v92, v92, v92 row_mirror row_mask:0xf bank_mask:0xf bound_ctrl:1
	v_pk_fma_f32 v[116:117], v[52:53], v[92:93], v[86:87] op_sel_hi:[1,0,1]
	v_pk_fma_f32 v[118:119], v[54:55], v[92:93], v[88:89] op_sel_hi:[1,0,1]
	v_add_f32_dpp v102, v102, v102 quad_perm:[1,0,3,2] row_mask:0xf bank_mask:0xf bound_ctrl:1
	s_waitcnt lgkmcnt(2)
	v_pk_mul_f32 v[84:85], v[116:117], v[68:69]
	v_pk_mul_f32 v[86:87], v[82:83], v[64:65] op_sel:[1,0]
	v_pk_fma_f32 v[84:85], v[118:119], v[70:71], v[84:85]
	v_pk_mul_f32 v[88:89], v[82:83], v[66:67] op_sel:[1,0]
	ds_read_b128 v[80:83], v106 offset:64
	v_add_f32_e32 v92, v84, v85
	v_pk_fma_f32 v[86:87], v[116:117], v[76:77], v[86:87]
	v_pk_mul_f32 v[90:91], v[116:117], v[40:41]
	v_add_f32_dpp v92, v92, v92 quad_perm:[1,0,3,2] row_mask:0xf bank_mask:0xf bound_ctrl:1
	v_pk_fma_f32 v[88:89], v[118:119], v[78:79], v[88:89]
	v_pk_fma_f32 v[90:91], v[118:119], v[42:43], v[90:91]
	s_waitcnt lgkmcnt(2)
; #define YRED4(dst) { \
;           float a0 = b3 ? p2 : p0, a1 = b3 ? p3 : p1; const float s0 = b3 ? p0 : p2, s1 = b3 ? p1 : p3; \
;           a0 += dppf<0x128>(s0); a1 += dppf<0x128>(s1); \
;           float cc = b2 ? a1 : a0; const float dd = b2 ? a0 : a1; \
;           cc += dppf<0x141>(dd); cc += dppf<0xB1>(cc); cc += dppf<0x4E>(cc); dst = cc; }
; __device__ __forceinline__ void phase_scan(KP p) {
;     ...
;         for (int g = 0; g < 8; ++g) {
;           const int st = g * 4;
;           SLD(C, st + 2); vnext = *(const float4*)(vb4 + st + 4);
;           __builtin_amdgcn_sched_barrier(0);
;           if (g > 0) { float yv; YRED4(yv); yb[(st - 4) * 16] = yv; }
;           SCOMP(A, vcur.x, q0);
;           SLD(D, st + 3);
;           __builtin_amdgcn_sched_barrier(0);
;           SCOMP(B, vcur.y, q1);
;           SLD(A, st + 4);
;           __builtin_amdgcn_sched_barrier(0);
;           SCOMP(C, vcur.z, q2);
;           SLD(B, st + 5);
;           __builtin_amdgcn_sched_barrier(0);
;           SCOMP(D, vcur.w, q3);
;           vcur = vnext; p0 = q0; p1 = q1; p2 = q2; p3 = q3;
;         }
	v_mfma_f32_32x32x16_bf16 v[20:35], v[112:115], v[124:127], 0
	v_add_f32_dpp v92, v92, v92 quad_perm:[2,3,0,1] row_mask:0xf bank_mask:0xf bound_ctrl:1
	v_add_f32_e32 v98, v90, v91
	ds_read_b128 v[108:111], v128 offset:9792
	v_add_f32_dpp v92, v92, v92 row_half_mirror row_mask:0xf bank_mask:0xf bound_ctrl:1
	ds_read_b128 v[36:39], v105 offset:22016
	v_add_f32_dpp v102, v102, v102 quad_perm:[2,3,0,1] row_mask:0xf bank_mask:0xf bound_ctrl:1
	v_add_f32_dpp v92, v92, v92 row_mirror row_mask:0xf bank_mask:0xf bound_ctrl:1
	v_pk_fma_f32 v[116:117], v[72:73], v[92:93], v[86:87] op_sel_hi:[1,0,1]
	v_pk_fma_f32 v[118:119], v[74:75], v[92:93], v[88:89] op_sel_hi:[1,0,1]
	ds_write_b32 v107, v102 offset:512
	s_waitcnt lgkmcnt(3)
	v_pk_mul_f32 v[84:85], v[116:117], v[8:9]
	v_pk_mul_f32 v[86:87], v[80:81], v[4:5] op_sel_hi:[0,1]
	v_pk_fma_f32 v[84:85], v[118:119], v[10:11], v[84:85]
	v_pk_mul_f32 v[88:89], v[80:81], v[6:7] op_sel_hi:[0,1]
	v_add_f32_e32 v92, v84, v85
	v_pk_fma_f32 v[86:87], v[116:117], v[16:17], v[86:87]
	v_pk_mul_f32 v[90:91], v[116:117], v[60:61]
	v_add_f32_dpp v92, v92, v92 quad_perm:[1,0,3,2] row_mask:0xf bank_mask:0xf bound_ctrl:1
	v_pk_fma_f32 v[88:89], v[118:119], v[18:19], v[88:89]
	v_pk_fma_f32 v[90:91], v[118:119], v[62:63], v[90:91]
	s_waitcnt lgkmcnt(2)
	v_mfma_f32_32x32x16_bf16 v[40:55], v[108:111], v[124:127], 0
	v_add_f32_dpp v92, v92, v92 quad_perm:[2,3,0,1] row_mask:0xf bank_mask:0xf bound_ctrl:1
	v_add_f32_e32 v99, v90, v91
	ds_read_b128 v[112:115], v128 offset:10336
	v_cndmask_b32_e64 v100, v98, v96, s[38:39]
	v_cndmask_b32_e64 v102, v96, v98, s[38:39]
	v_add_f32_dpp v92, v92, v92 row_half_mirror row_mask:0xf bank_mask:0xf bound_ctrl:1
	ds_read_b128 v[56:59], v105 offset:23296
	v_cndmask_b32_e64 v101, v99, v97, s[38:39]
	v_cndmask_b32_e64 v103, v97, v99, s[38:39]
	v_add_f32_dpp v92, v92, v92 row_mirror row_mask:0xf bank_mask:0xf bound_ctrl:1
	v_pk_fma_f32 v[116:117], v[12:13], v[92:93], v[86:87] op_sel_hi:[1,0,1]
	v_pk_fma_f32 v[118:119], v[14:15], v[92:93], v[88:89] op_sel_hi:[1,0,1]
	s_waitcnt lgkmcnt(3)
	v_pk_mul_f32 v[84:85], v[116:117], v[28:29]
	v_pk_mul_f32 v[86:87], v[80:81], v[24:25] op_sel:[1,0]
	v_pk_fma_f32 v[84:85], v[118:119], v[30:31], v[84:85]
	v_pk_mul_f32 v[88:89], v[80:81], v[26:27] op_sel:[1,0]
	v_add_f32_e32 v92, v84, v85
	v_pk_fma_f32 v[86:87], v[116:117], v[36:37], v[86:87]
	v_pk_mul_f32 v[90:91], v[116:117], v[0:1]
	v_add_f32_dpp v92, v92, v92 quad_perm:[1,0,3,2] row_mask:0xf bank_mask:0xf bound_ctrl:1
	v_pk_fma_f32 v[88:89], v[118:119], v[38:39], v[88:89]
	v_pk_fma_f32 v[90:91], v[118:119], v[2:3], v[90:91]
	s_waitcnt lgkmcnt(1)
	v_mfma_f32_32x32x16_bf16 v[60:75], v[112:115], v[124:127], 0
	v_add_f32_dpp v92, v92, v92 quad_perm:[2,3,0,1] row_mask:0xf bank_mask:0xf bound_ctrl:1
	v_add_f32_e32 v96, v90, v91
	ds_read_b128 v[108:111], v128 offset:10880
	v_add_f32_dpp v102, v102, v100 row_ror:8 row_mask:0xf bank_mask:0xf bound_ctrl:1
	v_add_f32_dpp v92, v92, v92 row_half_mirror row_mask:0xf bank_mask:0xf bound_ctrl:1
	ds_read_b128 v[76:79], v105 offset:24576
	v_add_f32_dpp v103, v103, v101 row_ror:8 row_mask:0xf bank_mask:0xf bound_ctrl:1
	v_add_f32_dpp v92, v92, v92 row_mirror row_mask:0xf bank_mask:0xf bound_ctrl:1
	v_cndmask_b32_e64 v104, v103, v102, s[40:41]
	v_cndmask_b32_e64 v102, v102, v103, s[40:41]
	v_pk_fma_f32 v[116:117], v[32:33], v[92:93], v[86:87] op_sel_hi:[1,0,1]
	v_pk_fma_f32 v[118:119], v[34:35], v[92:93], v[88:89] op_sel_hi:[1,0,1]
	s_waitcnt lgkmcnt(2)
	v_pk_mul_f32 v[84:85], v[116:117], v[48:49]
	v_pk_mul_f32 v[86:87], v[82:83], v[44:45] op_sel_hi:[0,1]
	v_pk_fma_f32 v[84:85], v[118:119], v[50:51], v[84:85]
	v_pk_mul_f32 v[88:89], v[82:83], v[46:47] op_sel_hi:[0,1]
	v_add_f32_e32 v92, v84, v85
	v_pk_fma_f32 v[86:87], v[116:117], v[56:57], v[86:87]
	v_pk_mul_f32 v[90:91], v[116:117], v[20:21]
	v_add_f32_dpp v92, v92, v92 quad_perm:[1,0,3,2] row_mask:0xf bank_mask:0xf bound_ctrl:1
	v_pk_fma_f32 v[88:89], v[118:119], v[58:59], v[88:89]
	v_pk_fma_f32 v[90:91], v[118:119], v[22:23], v[90:91]
	s_waitcnt lgkmcnt(1)
	v_mfma_f32_32x32x16_bf16 v[0:15], v[108:111], v[124:127], 0
	v_add_f32_dpp v92, v92, v92 quad_perm:[2,3,0,1] row_mask:0xf bank_mask:0xf bound_ctrl:1
	v_add_f32_e32 v97, v90, v91
	ds_read_b128 v[112:115], v128 offset:11424
	v_add_f32_dpp v92, v92, v92 row_half_mirror row_mask:0xf bank_mask:0xf bound_ctrl:1
	ds_read_b128 v[16:19], v105 offset:25856
	v_add_f32_dpp v102, v102, v104 row_half_mirror row_mask:0xf bank_mask:0xf bound_ctrl:1
	v_add_f32_dpp v92, v92, v92 row_mirror row_mask:0xf bank_mask:0xf bound_ctrl:1
	v_pk_fma_f32 v[116:117], v[52:53], v[92:93], v[86:87] op_sel_hi:[1,0,1]
	v_pk_fma_f32 v[118:119], v[54:55], v[92:93], v[88:89] op_sel_hi:[1,0,1]
	v_add_f32_dpp v102, v102, v102 quad_perm:[1,0,3,2] row_mask:0xf bank_mask:0xf bound_ctrl:1
	s_waitcnt lgkmcnt(2)
	v_pk_mul_f32 v[84:85], v[116:117], v[68:69]
	v_pk_mul_f32 v[86:87], v[82:83], v[64:65] op_sel:[1,0]
	v_pk_fma_f32 v[84:85], v[118:119], v[70:71], v[84:85]
	v_pk_mul_f32 v[88:89], v[82:83], v[66:67] op_sel:[1,0]
	ds_read_b128 v[80:83], v106 offset:80
	v_add_f32_e32 v92, v84, v85
	v_pk_fma_f32 v[86:87], v[116:117], v[76:77], v[86:87]
	v_pk_mul_f32 v[90:91], v[116:117], v[40:41]
	v_add_f32_dpp v92, v92, v92 quad_perm:[1,0,3,2] row_mask:0xf bank_mask:0xf bound_ctrl:1
	v_pk_fma_f32 v[88:89], v[118:119], v[78:79], v[88:89]
	v_pk_fma_f32 v[90:91], v[118:119], v[42:43], v[90:91]
	s_waitcnt lgkmcnt(2)
; #define YRED4(dst) { \
;           float a0 = b3 ? p2 : p0, a1 = b3 ? p3 : p1; const float s0 = b3 ? p0 : p2, s1 = b3 ? p1 : p3; \
;           a0 += dppf<0x128>(s0); a1 += dppf<0x128>(s1); \
;           float cc = b2 ? a1 : a0; const float dd = b2 ? a0 : a1; \
;           cc += dppf<0x141>(dd); cc += dppf<0xB1>(cc); cc += dppf<0x4E>(cc); dst = cc; }
; __device__ __forceinline__ void phase_scan(KP p) {
;     ...
;         for (int g = 0; g < 8; ++g) {
;           const int st = g * 4;
;           SLD(C, st + 2); vnext = *(const float4*)(vb4 + st + 4);
;           __builtin_amdgcn_sched_barrier(0);
;           if (g > 0) { float yv; YRED4(yv); yb[(st - 4) * 16] = yv; }
;           SCOMP(A, vcur.x, q0);
;           SLD(D, st + 3);
;           __builtin_amdgcn_sched_barrier(0);
;           SCOMP(B, vcur.y, q1);
;           SLD(A, st + 4);
;           __builtin_amdgcn_sched_barrier(0);
;           SCOMP(C, vcur.z, q2);
;           SLD(B, st + 5);
;           __builtin_amdgcn_sched_barrier(0);
;           SCOMP(D, vcur.w, q3);
;           vcur = vnext; p0 = q0; p1 = q1; p2 = q2; p3 = q3;
;         }
	v_mfma_f32_32x32x16_bf16 v[20:35], v[112:115], v[124:127], 0
	v_add_f32_dpp v92, v92, v92 quad_perm:[2,3,0,1] row_mask:0xf bank_mask:0xf bound_ctrl:1
	v_add_f32_e32 v98, v90, v91
	ds_read_b128 v[108:111], v128 offset:11968
	v_add_f32_dpp v92, v92, v92 row_half_mirror row_mask:0xf bank_mask:0xf bound_ctrl:1
	ds_read_b128 v[36:39], v105 offset:27136
	v_add_f32_dpp v102, v102, v102 quad_perm:[2,3,0,1] row_mask:0xf bank_mask:0xf bound_ctrl:1
	v_add_f32_dpp v92, v92, v92 row_mirror row_mask:0xf bank_mask:0xf bound_ctrl:1
	v_pk_fma_f32 v[116:117], v[72:73], v[92:93], v[86:87] op_sel_hi:[1,0,1]
	v_pk_fma_f32 v[118:119], v[74:75], v[92:93], v[88:89] op_sel_hi:[1,0,1]
	ds_write_b32 v107, v102 offset:768
	s_waitcnt lgkmcnt(3)
	v_pk_mul_f32 v[84:85], v[116:117], v[8:9]
	v_pk_mul_f32 v[86:87], v[80:81], v[4:5] op_sel_hi:[0,1]
	v_pk_fma_f32 v[84:85], v[118:119], v[10:11], v[84:85]
	v_pk_mul_f32 v[88:89], v[80:81], v[6:7] op_sel_hi:[0,1]
	v_add_f32_e32 v92, v84, v85
	v_pk_fma_f32 v[86:87], v[116:117], v[16:17], v[86:87]
	v_pk_mul_f32 v[90:91], v[116:117], v[60:61]
	v_add_f32_dpp v92, v92, v92 quad_perm:[1,0,3,2] row_mask:0xf bank_mask:0xf bound_ctrl:1
	v_pk_fma_f32 v[88:89], v[118:119], v[18:19], v[88:89]
	v_pk_fma_f32 v[90:91], v[118:119], v[62:63], v[90:91]
	s_waitcnt lgkmcnt(2)
	v_mfma_f32_32x32x16_bf16 v[40:55], v[108:111], v[124:127], 0
	v_add_f32_dpp v92, v92, v92 quad_perm:[2,3,0,1] row_mask:0xf bank_mask:0xf bound_ctrl:1
	v_add_f32_e32 v99, v90, v91
	ds_read_b128 v[112:115], v128 offset:12512
	v_cndmask_b32_e64 v100, v98, v96, s[38:39]
	v_cndmask_b32_e64 v102, v96, v98, s[38:39]
	v_add_f32_dpp v92, v92, v92 row_half_mirror row_mask:0xf bank_mask:0xf bound_ctrl:1
	ds_read_b128 v[56:59], v105 offset:28416
	v_cndmask_b32_e64 v101, v99, v97, s[38:39]
	v_cndmask_b32_e64 v103, v97, v99, s[38:39]
	v_add_f32_dpp v92, v92, v92 row_mirror row_mask:0xf bank_mask:0xf bound_ctrl:1
	v_pk_fma_f32 v[116:117], v[12:13], v[92:93], v[86:87] op_sel_hi:[1,0,1]
	v_pk_fma_f32 v[118:119], v[14:15], v[92:93], v[88:89] op_sel_hi:[1,0,1]
	s_waitcnt lgkmcnt(3)
	v_pk_mul_f32 v[84:85], v[116:117], v[28:29]
	v_pk_mul_f32 v[86:87], v[80:81], v[24:25] op_sel:[1,0]
	v_pk_fma_f32 v[84:85], v[118:119], v[30:31], v[84:85]
	v_pk_mul_f32 v[88:89], v[80:81], v[26:27] op_sel:[1,0]
	v_add_f32_e32 v92, v84, v85
	v_pk_fma_f32 v[86:87], v[116:117], v[36:37], v[86:87]
	v_pk_mul_f32 v[90:91], v[116:117], v[0:1]
	v_add_f32_dpp v92, v92, v92 quad_perm:[1,0,3,2] row_mask:0xf bank_mask:0xf bound_ctrl:1
	v_pk_fma_f32 v[88:89], v[118:119], v[38:39], v[88:89]
	v_pk_fma_f32 v[90:91], v[118:119], v[2:3], v[90:91]
	s_waitcnt lgkmcnt(1)
	v_mfma_f32_32x32x16_bf16 v[60:75], v[112:115], v[124:127], 0
	v_add_f32_dpp v92, v92, v92 quad_perm:[2,3,0,1] row_mask:0xf bank_mask:0xf bound_ctrl:1
	v_add_f32_e32 v96, v90, v91
	ds_read_b128 v[108:111], v128 offset:13056
	v_add_f32_dpp v102, v102, v100 row_ror:8 row_mask:0xf bank_mask:0xf bound_ctrl:1
	v_add_f32_dpp v92, v92, v92 row_half_mirror row_mask:0xf bank_mask:0xf bound_ctrl:1
	ds_read_b128 v[76:79], v105 offset:29696
	v_add_f32_dpp v103, v103, v101 row_ror:8 row_mask:0xf bank_mask:0xf bound_ctrl:1
	v_add_f32_dpp v92, v92, v92 row_mirror row_mask:0xf bank_mask:0xf bound_ctrl:1
	v_cndmask_b32_e64 v104, v103, v102, s[40:41]
	v_cndmask_b32_e64 v102, v102, v103, s[40:41]
	v_pk_fma_f32 v[116:117], v[32:33], v[92:93], v[86:87] op_sel_hi:[1,0,1]
	v_pk_fma_f32 v[118:119], v[34:35], v[92:93], v[88:89] op_sel_hi:[1,0,1]
	s_waitcnt lgkmcnt(2)
	v_pk_mul_f32 v[84:85], v[116:117], v[48:49]
	v_pk_mul_f32 v[86:87], v[82:83], v[44:45] op_sel_hi:[0,1]
	v_pk_fma_f32 v[84:85], v[118:119], v[50:51], v[84:85]
	v_pk_mul_f32 v[88:89], v[82:83], v[46:47] op_sel_hi:[0,1]
	v_add_f32_e32 v92, v84, v85
	v_pk_fma_f32 v[86:87], v[116:117], v[56:57], v[86:87]
	v_pk_mul_f32 v[90:91], v[116:117], v[20:21]
	v_add_f32_dpp v92, v92, v92 quad_perm:[1,0,3,2] row_mask:0xf bank_mask:0xf bound_ctrl:1
	v_pk_fma_f32 v[88:89], v[118:119], v[58:59], v[88:89]
	v_pk_fma_f32 v[90:91], v[118:119], v[22:23], v[90:91]
	s_waitcnt lgkmcnt(1)
	v_mfma_f32_32x32x16_bf16 v[0:15], v[108:111], v[124:127], 0
	v_add_f32_dpp v92, v92, v92 quad_perm:[2,3,0,1] row_mask:0xf bank_mask:0xf bound_ctrl:1
	v_add_f32_e32 v97, v90, v91
	ds_read_b128 v[112:115], v128 offset:13600
	v_add_f32_dpp v92, v92, v92 row_half_mirror row_mask:0xf bank_mask:0xf bound_ctrl:1
	ds_read_b128 v[16:19], v105 offset:30976
	v_add_f32_dpp v102, v102, v104 row_half_mirror row_mask:0xf bank_mask:0xf bound_ctrl:1
	v_add_f32_dpp v92, v92, v92 row_mirror row_mask:0xf bank_mask:0xf bound_ctrl:1
	v_pk_fma_f32 v[116:117], v[52:53], v[92:93], v[86:87] op_sel_hi:[1,0,1]
	v_pk_fma_f32 v[118:119], v[54:55], v[92:93], v[88:89] op_sel_hi:[1,0,1]
	v_add_f32_dpp v102, v102, v102 quad_perm:[1,0,3,2] row_mask:0xf bank_mask:0xf bound_ctrl:1
	s_waitcnt lgkmcnt(2)
	v_pk_mul_f32 v[84:85], v[116:117], v[68:69]
	v_pk_mul_f32 v[86:87], v[82:83], v[64:65] op_sel:[1,0]
	v_pk_fma_f32 v[84:85], v[118:119], v[70:71], v[84:85]
	v_pk_mul_f32 v[88:89], v[82:83], v[66:67] op_sel:[1,0]
	ds_read_b128 v[80:83], v106 offset:96
	v_add_f32_e32 v92, v84, v85
	v_pk_fma_f32 v[86:87], v[116:117], v[76:77], v[86:87]
	v_pk_mul_f32 v[90:91], v[116:117], v[40:41]
	v_add_f32_dpp v92, v92, v92 quad_perm:[1,0,3,2] row_mask:0xf bank_mask:0xf bound_ctrl:1
	v_pk_fma_f32 v[88:89], v[118:119], v[78:79], v[88:89]
	v_pk_fma_f32 v[90:91], v[118:119], v[42:43], v[90:91]
	s_waitcnt lgkmcnt(2)
	v_mfma_f32_32x32x16_bf16 v[20:35], v[112:115], v[124:127], 0
	v_add_f32_dpp v92, v92, v92 quad_perm:[2,3,0,1] row_mask:0xf bank_mask:0xf bound_ctrl:1
	v_add_f32_e32 v98, v90, v91
	ds_read_b128 v[108:111], v128 offset:14144
	v_add_f32_dpp v92, v92, v92 row_half_mirror row_mask:0xf bank_mask:0xf bound_ctrl:1
	ds_read_b128 v[36:39], v105 offset:32256
	v_add_f32_dpp v102, v102, v102 quad_perm:[2,3,0,1] row_mask:0xf bank_mask:0xf bound_ctrl:1
	v_add_f32_dpp v92, v92, v92 row_mirror row_mask:0xf bank_mask:0xf bound_ctrl:1
	v_pk_fma_f32 v[116:117], v[72:73], v[92:93], v[86:87] op_sel_hi:[1,0,1]
	v_pk_fma_f32 v[118:119], v[74:75], v[92:93], v[88:89] op_sel_hi:[1,0,1]
	ds_write_b32 v107, v102 offset:1024
	s_barrier
; #define YRED4(dst) { \
;           float a0 = b3 ? p2 : p0, a1 = b3 ? p3 : p1; const float s0 = b3 ? p0 : p2, s1 = b3 ? p1 : p3; \
;           a0 += dppf<0x128>(s0); a1 += dppf<0x128>(s1); \
;           float cc = b2 ? a1 : a0; const float dd = b2 ? a0 : a1; \
;           cc += dppf<0x141>(dd); cc += dppf<0xB1>(cc); cc += dppf<0x4E>(cc); dst = cc; }
; __device__ __forceinline__ void phase_scan(KP p) {
;     ...
;         for (int g = 0; g < 8; ++g) {
;           const int st = g * 4;
;           SLD(C, st + 2); vnext = *(const float4*)(vb4 + st + 4);
;           __builtin_amdgcn_sched_barrier(0);
;           if (g > 0) { float yv; YRED4(yv); yb[(st - 4) * 16] = yv; }
;           SCOMP(A, vcur.x, q0);
;           SLD(D, st + 3);
;           __builtin_amdgcn_sched_barrier(0);
;           SCOMP(B, vcur.y, q1);
;           SLD(A, st + 4);
;           __builtin_amdgcn_sched_barrier(0);
;           SCOMP(C, vcur.z, q2);
;           SLD(B, st + 5);
;           __builtin_amdgcn_sched_barrier(0);
;           SCOMP(D, vcur.w, q3);
;           vcur = vnext; p0 = q0; p1 = q1; p2 = q2; p3 = q3;
;         }
	s_xor_b32 s19, s70, 1
	s_mul_i32 s19, s19, 0x4400
	v_add_u32_e32 v93, s19, v129
	s_xor_b32 s19, s70, 1
	s_mul_i32 s19, s19, 0xa000
	v_add_u32_e32 v94, s19, v120
	s_xor_b32 s19, s70, 1
	v_lshl_add_u32 v95, s19, 11, v121
	s_waitcnt lgkmcnt(3)
	v_pk_mul_f32 v[84:85], v[116:117], v[8:9]
	v_pk_mul_f32 v[86:87], v[80:81], v[4:5] op_sel_hi:[0,1]
	v_pk_fma_f32 v[84:85], v[118:119], v[10:11], v[84:85]
	v_pk_mul_f32 v[88:89], v[80:81], v[6:7] op_sel_hi:[0,1]
	v_add_f32_e32 v92, v84, v85
	v_pk_fma_f32 v[86:87], v[116:117], v[16:17], v[86:87]
	v_pk_mul_f32 v[90:91], v[116:117], v[60:61]
	v_add_f32_dpp v92, v92, v92 quad_perm:[1,0,3,2] row_mask:0xf bank_mask:0xf bound_ctrl:1
	v_pk_fma_f32 v[88:89], v[118:119], v[18:19], v[88:89]
	v_pk_fma_f32 v[90:91], v[118:119], v[62:63], v[90:91]
	s_waitcnt lgkmcnt(2)
	v_mfma_f32_32x32x16_bf16 v[40:55], v[108:111], v[124:127], 0
	v_add_f32_dpp v92, v92, v92 quad_perm:[2,3,0,1] row_mask:0xf bank_mask:0xf bound_ctrl:1
	v_add_f32_e32 v99, v90, v91
	ds_read_b128 v[112:115], v128 offset:14688
	v_cndmask_b32_e64 v100, v98, v96, s[38:39]
	v_cndmask_b32_e64 v102, v96, v98, s[38:39]
	v_add_f32_dpp v92, v92, v92 row_half_mirror row_mask:0xf bank_mask:0xf bound_ctrl:1
	ds_read_b128 v[56:59], v105 offset:33536
	v_cndmask_b32_e64 v101, v99, v97, s[38:39]
	v_cndmask_b32_e64 v103, v97, v99, s[38:39]
	v_add_f32_dpp v92, v92, v92 row_mirror row_mask:0xf bank_mask:0xf bound_ctrl:1
	v_pk_fma_f32 v[116:117], v[12:13], v[92:93], v[86:87] op_sel_hi:[1,0,1]
	v_pk_fma_f32 v[118:119], v[14:15], v[92:93], v[88:89] op_sel_hi:[1,0,1]
	s_waitcnt lgkmcnt(3)
	v_pk_mul_f32 v[84:85], v[116:117], v[28:29]
	v_pk_mul_f32 v[86:87], v[80:81], v[24:25] op_sel:[1,0]
	v_pk_fma_f32 v[84:85], v[118:119], v[30:31], v[84:85]
	v_pk_mul_f32 v[88:89], v[80:81], v[26:27] op_sel:[1,0]
	v_add_f32_e32 v92, v84, v85
	v_pk_fma_f32 v[86:87], v[116:117], v[36:37], v[86:87]
	v_pk_mul_f32 v[90:91], v[116:117], v[0:1]
	v_add_f32_dpp v92, v92, v92 quad_perm:[1,0,3,2] row_mask:0xf bank_mask:0xf bound_ctrl:1
	v_pk_fma_f32 v[88:89], v[118:119], v[38:39], v[88:89]
	v_pk_fma_f32 v[90:91], v[118:119], v[2:3], v[90:91]
	s_waitcnt lgkmcnt(1)
	v_mfma_f32_32x32x16_bf16 v[60:75], v[112:115], v[124:127], 0
	v_add_f32_dpp v92, v92, v92 quad_perm:[2,3,0,1] row_mask:0xf bank_mask:0xf bound_ctrl:1
	v_add_f32_e32 v96, v90, v91
	ds_read_b128 v[108:111], v128 offset:15232
	v_add_f32_dpp v102, v102, v100 row_ror:8 row_mask:0xf bank_mask:0xf bound_ctrl:1
	v_add_f32_dpp v92, v92, v92 row_half_mirror row_mask:0xf bank_mask:0xf bound_ctrl:1
	ds_read_b128 v[76:79], v105 offset:34816
	v_add_f32_dpp v103, v103, v101 row_ror:8 row_mask:0xf bank_mask:0xf bound_ctrl:1
	v_add_f32_dpp v92, v92, v92 row_mirror row_mask:0xf bank_mask:0xf bound_ctrl:1
	v_cndmask_b32_e64 v104, v103, v102, s[40:41]
	v_cndmask_b32_e64 v102, v102, v103, s[40:41]
	v_pk_fma_f32 v[116:117], v[32:33], v[92:93], v[86:87] op_sel_hi:[1,0,1]
	v_pk_fma_f32 v[118:119], v[34:35], v[92:93], v[88:89] op_sel_hi:[1,0,1]
	s_waitcnt lgkmcnt(2)
	v_pk_mul_f32 v[84:85], v[116:117], v[48:49]
	v_pk_mul_f32 v[86:87], v[82:83], v[44:45] op_sel_hi:[0,1]
	v_pk_fma_f32 v[84:85], v[118:119], v[50:51], v[84:85]
	v_pk_mul_f32 v[88:89], v[82:83], v[46:47] op_sel_hi:[0,1]
	v_add_f32_e32 v92, v84, v85
	v_pk_fma_f32 v[86:87], v[116:117], v[56:57], v[86:87]
	v_pk_mul_f32 v[90:91], v[116:117], v[20:21]
	v_add_f32_dpp v92, v92, v92 quad_perm:[1,0,3,2] row_mask:0xf bank_mask:0xf bound_ctrl:1
	v_pk_fma_f32 v[88:89], v[118:119], v[58:59], v[88:89]
	v_pk_fma_f32 v[90:91], v[118:119], v[22:23], v[90:91]
	s_waitcnt lgkmcnt(1)
	v_mfma_f32_32x32x16_bf16 v[0:15], v[108:111], v[124:127], 0
	v_add_f32_dpp v92, v92, v92 quad_perm:[2,3,0,1] row_mask:0xf bank_mask:0xf bound_ctrl:1
	v_add_f32_e32 v97, v90, v91
	ds_read_b128 v[112:115], v128 offset:15776
	v_add_f32_dpp v92, v92, v92 row_half_mirror row_mask:0xf bank_mask:0xf bound_ctrl:1
	ds_read_b128 v[16:19], v105 offset:36096
	v_add_f32_dpp v102, v102, v104 row_half_mirror row_mask:0xf bank_mask:0xf bound_ctrl:1
	v_add_f32_dpp v92, v92, v92 row_mirror row_mask:0xf bank_mask:0xf bound_ctrl:1
	v_pk_fma_f32 v[116:117], v[52:53], v[92:93], v[86:87] op_sel_hi:[1,0,1]
	v_pk_fma_f32 v[118:119], v[54:55], v[92:93], v[88:89] op_sel_hi:[1,0,1]
	v_add_f32_dpp v102, v102, v102 quad_perm:[1,0,3,2] row_mask:0xf bank_mask:0xf bound_ctrl:1
	s_waitcnt lgkmcnt(2)
	v_pk_mul_f32 v[84:85], v[116:117], v[68:69]
	v_pk_mul_f32 v[86:87], v[82:83], v[64:65] op_sel:[1,0]
	v_pk_fma_f32 v[84:85], v[118:119], v[70:71], v[84:85]
	v_pk_mul_f32 v[88:89], v[82:83], v[66:67] op_sel:[1,0]
	ds_read_b128 v[80:83], v106 offset:112
	v_add_f32_e32 v92, v84, v85
	v_pk_fma_f32 v[86:87], v[116:117], v[76:77], v[86:87]
	v_pk_mul_f32 v[90:91], v[116:117], v[40:41]
	v_add_f32_dpp v92, v92, v92 quad_perm:[1,0,3,2] row_mask:0xf bank_mask:0xf bound_ctrl:1
	v_pk_fma_f32 v[88:89], v[118:119], v[78:79], v[88:89]
	v_pk_fma_f32 v[90:91], v[118:119], v[42:43], v[90:91]
	s_waitcnt lgkmcnt(2)
	v_mfma_f32_32x32x16_bf16 v[20:35], v[112:115], v[124:127], 0
	v_add_f32_dpp v92, v92, v92 quad_perm:[2,3,0,1] row_mask:0xf bank_mask:0xf bound_ctrl:1
	v_add_f32_e32 v98, v90, v91
	ds_read_b128 v[108:111], v128 offset:16320
	v_add_f32_dpp v92, v92, v92 row_half_mirror row_mask:0xf bank_mask:0xf bound_ctrl:1
	ds_read_b128 v[36:39], v105 offset:37376
	v_add_f32_dpp v102, v102, v102 quad_perm:[2,3,0,1] row_mask:0xf bank_mask:0xf bound_ctrl:1
	v_add_f32_dpp v92, v92, v92 row_mirror row_mask:0xf bank_mask:0xf bound_ctrl:1
	v_pk_fma_f32 v[116:117], v[72:73], v[92:93], v[86:87] op_sel_hi:[1,0,1]
	v_pk_fma_f32 v[118:119], v[74:75], v[92:93], v[88:89] op_sel_hi:[1,0,1]
	ds_write_b32 v107, v102 offset:1280
	s_waitcnt lgkmcnt(3)
; #define YRED4(dst) { \
;           float a0 = b3 ? p2 : p0, a1 = b3 ? p3 : p1; const float s0 = b3 ? p0 : p2, s1 = b3 ? p1 : p3; \
;           a0 += dppf<0x128>(s0); a1 += dppf<0x128>(s1); \
;           float cc = b2 ? a1 : a0; const float dd = b2 ? a0 : a1; \
;           cc += dppf<0x141>(dd); cc += dppf<0xB1>(cc); cc += dppf<0x4E>(cc); dst = cc; }
; __device__ __forceinline__ void phase_scan(KP p) {
;     ...
;         for (int g = 0; g < 8; ++g) {
;           const int st = g * 4;
;           SLD(C, st + 2); vnext = *(const float4*)(vb4 + st + 4);
;           __builtin_amdgcn_sched_barrier(0);
;           if (g > 0) { float yv; YRED4(yv); yb[(st - 4) * 16] = yv; }
;           SCOMP(A, vcur.x, q0);
;           SLD(D, st + 3);
;           __builtin_amdgcn_sched_barrier(0);
;           SCOMP(B, vcur.y, q1);
;           SLD(A, st + 4);
;           __builtin_amdgcn_sched_barrier(0);
;           SCOMP(C, vcur.z, q2);
;           SLD(B, st + 5);
;           __builtin_amdgcn_sched_barrier(0);
;           SCOMP(D, vcur.w, q3);
;           vcur = vnext; p0 = q0; p1 = q1; p2 = q2; p3 = q3;
;         }
;         { float yv; YRED4(yv); yb[28 * 16] = yv; }
;     ...
;       }
;       asm volatile("s_waitcnt lgkmcnt(0)" ::: "memory");
;       __builtin_amdgcn_s_barrier();
	v_pk_mul_f32 v[84:85], v[116:117], v[8:9]
	v_pk_mul_f32 v[86:87], v[80:81], v[4:5] op_sel_hi:[0,1]
	v_pk_fma_f32 v[84:85], v[118:119], v[10:11], v[84:85]
	v_pk_mul_f32 v[88:89], v[80:81], v[6:7] op_sel_hi:[0,1]
	v_add_f32_e32 v92, v84, v85
	v_pk_fma_f32 v[86:87], v[116:117], v[16:17], v[86:87]
	v_pk_mul_f32 v[90:91], v[116:117], v[60:61]
	v_add_f32_dpp v92, v92, v92 quad_perm:[1,0,3,2] row_mask:0xf bank_mask:0xf bound_ctrl:1
	v_pk_fma_f32 v[88:89], v[118:119], v[18:19], v[88:89]
	v_pk_fma_f32 v[90:91], v[118:119], v[62:63], v[90:91]
	s_waitcnt lgkmcnt(2)
	v_mfma_f32_32x32x16_bf16 v[40:55], v[108:111], v[124:127], 0
	v_add_f32_dpp v92, v92, v92 quad_perm:[2,3,0,1] row_mask:0xf bank_mask:0xf bound_ctrl:1
	v_add_f32_e32 v99, v90, v91
	ds_read_b128 v[112:115], v128 offset:16864
	v_cndmask_b32_e64 v100, v98, v96, s[38:39]
	v_cndmask_b32_e64 v102, v96, v98, s[38:39]
	v_add_f32_dpp v92, v92, v92 row_half_mirror row_mask:0xf bank_mask:0xf bound_ctrl:1
	ds_read_b128 v[56:59], v105 offset:38656
	v_cndmask_b32_e64 v101, v99, v97, s[38:39]
	v_cndmask_b32_e64 v103, v97, v99, s[38:39]
	v_add_f32_dpp v92, v92, v92 row_mirror row_mask:0xf bank_mask:0xf bound_ctrl:1
	v_pk_fma_f32 v[116:117], v[12:13], v[92:93], v[86:87] op_sel_hi:[1,0,1]
	v_pk_fma_f32 v[118:119], v[14:15], v[92:93], v[88:89] op_sel_hi:[1,0,1]
	s_waitcnt lgkmcnt(3)
	v_pk_mul_f32 v[84:85], v[116:117], v[28:29]
	v_pk_mul_f32 v[86:87], v[80:81], v[24:25] op_sel:[1,0]
	v_pk_fma_f32 v[84:85], v[118:119], v[30:31], v[84:85]
	v_pk_mul_f32 v[88:89], v[80:81], v[26:27] op_sel:[1,0]
	v_add_f32_e32 v92, v84, v85
	v_pk_fma_f32 v[86:87], v[116:117], v[36:37], v[86:87]
	v_pk_mul_f32 v[90:91], v[116:117], v[0:1]
	v_add_f32_dpp v92, v92, v92 quad_perm:[1,0,3,2] row_mask:0xf bank_mask:0xf bound_ctrl:1
	v_pk_fma_f32 v[88:89], v[118:119], v[38:39], v[88:89]
	v_pk_fma_f32 v[90:91], v[118:119], v[2:3], v[90:91]
	s_waitcnt lgkmcnt(1)
	v_mfma_f32_32x32x16_bf16 v[60:75], v[112:115], v[124:127], 0
	v_add_f32_dpp v92, v92, v92 quad_perm:[2,3,0,1] row_mask:0xf bank_mask:0xf bound_ctrl:1
	v_add_f32_e32 v96, v90, v91
	ds_read_b128 v[108:111], v93
	v_add_f32_dpp v102, v102, v100 row_ror:8 row_mask:0xf bank_mask:0xf bound_ctrl:1
	v_add_f32_dpp v92, v92, v92 row_half_mirror row_mask:0xf bank_mask:0xf bound_ctrl:1
	ds_read_b128 v[76:79], v105 offset:39936
	v_add_f32_dpp v103, v103, v101 row_ror:8 row_mask:0xf bank_mask:0xf bound_ctrl:1
	v_add_f32_dpp v92, v92, v92 row_mirror row_mask:0xf bank_mask:0xf bound_ctrl:1
	v_cndmask_b32_e64 v104, v103, v102, s[40:41]
	v_cndmask_b32_e64 v102, v102, v103, s[40:41]
	v_pk_fma_f32 v[116:117], v[32:33], v[92:93], v[86:87] op_sel_hi:[1,0,1]
	v_pk_fma_f32 v[118:119], v[34:35], v[92:93], v[88:89] op_sel_hi:[1,0,1]
	s_waitcnt lgkmcnt(2)
	v_pk_mul_f32 v[84:85], v[116:117], v[48:49]
	v_pk_mul_f32 v[86:87], v[82:83], v[44:45] op_sel_hi:[0,1]
	v_pk_fma_f32 v[84:85], v[118:119], v[50:51], v[84:85]
	v_pk_mul_f32 v[88:89], v[82:83], v[46:47] op_sel_hi:[0,1]
	v_add_f32_e32 v92, v84, v85
	v_pk_fma_f32 v[86:87], v[116:117], v[56:57], v[86:87]
	v_pk_mul_f32 v[90:91], v[116:117], v[20:21]
	v_add_f32_dpp v92, v92, v92 quad_perm:[1,0,3,2] row_mask:0xf bank_mask:0xf bound_ctrl:1
	v_pk_fma_f32 v[88:89], v[118:119], v[58:59], v[88:89]
	v_pk_fma_f32 v[90:91], v[118:119], v[22:23], v[90:91]
	s_waitcnt lgkmcnt(1)
	v_mfma_f32_32x32x16_bf16 v[0:15], v[108:111], v[124:127], 0
	v_add_f32_dpp v92, v92, v92 quad_perm:[2,3,0,1] row_mask:0xf bank_mask:0xf bound_ctrl:1
	v_add_f32_e32 v97, v90, v91
	ds_read_b128 v[112:115], v93 offset:544
	v_add_f32_dpp v92, v92, v92 row_half_mirror row_mask:0xf bank_mask:0xf bound_ctrl:1
	ds_read_b128 v[16:19], v94 offset:256
	v_add_f32_dpp v102, v102, v104 row_half_mirror row_mask:0xf bank_mask:0xf bound_ctrl:1
	v_add_f32_dpp v92, v92, v92 row_mirror row_mask:0xf bank_mask:0xf bound_ctrl:1
	v_pk_fma_f32 v[116:117], v[52:53], v[92:93], v[86:87] op_sel_hi:[1,0,1]
	v_pk_fma_f32 v[118:119], v[54:55], v[92:93], v[88:89] op_sel_hi:[1,0,1]
	v_add_f32_dpp v102, v102, v102 quad_perm:[1,0,3,2] row_mask:0xf bank_mask:0xf bound_ctrl:1
	s_waitcnt lgkmcnt(2)
	v_pk_mul_f32 v[84:85], v[116:117], v[68:69]
	v_pk_mul_f32 v[86:87], v[82:83], v[64:65] op_sel:[1,0]
	v_pk_fma_f32 v[84:85], v[118:119], v[70:71], v[84:85]
	v_pk_mul_f32 v[88:89], v[82:83], v[66:67] op_sel:[1,0]
	ds_read_b128 v[80:83], v95
	v_add_f32_e32 v92, v84, v85
	v_pk_fma_f32 v[86:87], v[116:117], v[76:77], v[86:87]
	v_pk_mul_f32 v[90:91], v[116:117], v[40:41]
	v_add_f32_dpp v92, v92, v92 quad_perm:[1,0,3,2] row_mask:0xf bank_mask:0xf bound_ctrl:1
	v_pk_fma_f32 v[88:89], v[118:119], v[78:79], v[88:89]
	v_pk_fma_f32 v[90:91], v[118:119], v[42:43], v[90:91]
	s_waitcnt lgkmcnt(2)
	v_mfma_f32_32x32x16_bf16 v[20:35], v[112:115], v[124:127], 0
	v_add_f32_dpp v92, v92, v92 quad_perm:[2,3,0,1] row_mask:0xf bank_mask:0xf bound_ctrl:1
	v_add_f32_e32 v98, v90, v91
	ds_read_b128 v[108:111], v93 offset:1088
	v_add_f32_dpp v92, v92, v92 row_half_mirror row_mask:0xf bank_mask:0xf bound_ctrl:1
	ds_read_b128 v[36:39], v94 offset:1536
	v_add_f32_dpp v102, v102, v102 quad_perm:[2,3,0,1] row_mask:0xf bank_mask:0xf bound_ctrl:1
	v_add_f32_dpp v92, v92, v92 row_mirror row_mask:0xf bank_mask:0xf bound_ctrl:1
	v_pk_fma_f32 v[116:117], v[72:73], v[92:93], v[86:87] op_sel_hi:[1,0,1]
	v_pk_fma_f32 v[118:119], v[74:75], v[92:93], v[88:89] op_sel_hi:[1,0,1]
	ds_write_b32 v107, v102 offset:1536
	v_cndmask_b32_e64 v100, v98, v96, s[38:39]
	v_pk_mul_f32 v[90:91], v[116:117], v[60:61]
	v_cndmask_b32_e64 v102, v96, v98, s[38:39]
	v_pk_fma_f32 v[90:91], v[118:119], v[62:63], v[90:91]
	s_nop 0
	v_add_f32_e32 v99, v90, v91
	v_add_f32_dpp v102, v102, v100 row_ror:8 row_mask:0xf bank_mask:0xf bound_ctrl:1
	v_cndmask_b32_e64 v101, v99, v97, s[38:39]
	v_cndmask_b32_e64 v103, v97, v99, s[38:39]
	s_nop 1
	v_add_f32_dpp v103, v103, v101 row_ror:8 row_mask:0xf bank_mask:0xf bound_ctrl:1
	v_cndmask_b32_e64 v104, v103, v102, s[40:41]
	v_cndmask_b32_e64 v102, v102, v103, s[40:41]
	s_nop 1
	v_add_f32_dpp v102, v102, v104 row_half_mirror row_mask:0xf bank_mask:0xf bound_ctrl:1
	s_nop 1
	v_add_f32_dpp v102, v102, v102 quad_perm:[1,0,3,2] row_mask:0xf bank_mask:0xf bound_ctrl:1
	s_nop 1
	v_add_f32_dpp v102, v102, v102 quad_perm:[2,3,0,1] row_mask:0xf bank_mask:0xf bound_ctrl:1
	ds_write_b32 v107, v102 offset:1792
	s_branch .LBB0_755
.Lscan_skipmid:
	s_barrier
	s_branch .LBB0_755
